# attention PV: counted lgkmcnt(6) before each MFMA of the first three d0 groups instead of lgkmcnt(0) per group (wait at first consumer); plus no-mask fast path and GEMM edits
# baseline (speedup 1.0000x reference)
; __device__ __forceinline__ void finishSM(f32x16& p0, f32x16& p1, float alpha, float& l_reg, bf16x8& pa0, bf16x8& pa1, bf16x8& pa2, bf16x8& pa3) {
; #pragma unroll
;     for (int r = 0; r < 16; ++r) p1[r] = __builtin_amdgcn_exp2f(p1[r]);
;     float ps = 0;
; #pragma unroll
;     for (int r = 0; r < 16; ++r) ps += p0[r];
; #pragma unroll
;     for (int r = 0; r < 16; ++r) ps += p1[r];
;     { auto rr = __builtin_amdgcn_permlane32_swap(__float_as_uint(ps), __float_as_uint(ps), false, false);
;       ps = __uint_as_float(rr[0]) + __uint_as_float(rr[1]); }
;     l_reg = l_reg * alpha + ps;
;     ...
;     PK4(p0, 0, pa0); PK4(p0, 8, pa1); PK4(p1, 0, pa2); PK4(p1, 8, pa3);
;     ...
; }
; __device__ __forceinline__ void qkt(f32x16& p0, f32x16& p1, const char* Ks, const bf16x8* qr, int r32, int hi) {
;     p0 = f32x16{}; p1 = f32x16{};
; #pragma unroll
;     for (int d0 = 0; d0 < 8; ++d0) { int cb = (d0 * 16 + hi * 8) * 2;
;         bf16x8 b0 = *reinterpret_cast<const bf16x8*>(Ks + KSWZ(r32, cb));
;         bf16x8 b1 = *reinterpret_cast<const bf16x8*>(Ks + KSWZ(32 + r32, cb));
;         p0 = __builtin_amdgcn_mfma_f32_32x32x16_bf16(b0, qr[d0], p0, 0, 0, 0);
;         p1 = __builtin_amdgcn_mfma_f32_32x32x16_bf16(b1, qr[d0], p1, 0, 0, 0); }
; }
.LBB0_280:
	s_add_i32 s9, s25, -1
	ds_read_b128 v[64:67], v215 offset:49152
	ds_read_b128 v[68:71], v215 offset:57344
	ds_read_b128 v[224:227], v222 offset:49152
	ds_read_b128 v[236:239], v222 offset:57344
	v_add_f32_e32 v160, 0, v174
	v_add_f32_e32 v160, v198, v160
	s_waitcnt lgkmcnt(3)
	v_mfma_f32_32x32x16_bf16 v[80:95], v[64:67], v[124:127], 0
	v_add_f32_e32 v160, v161, v160
	v_add_f32_e32 v160, v175, v160
	v_add_f32_e32 v160, v162, v160
	v_add_f32_e32 v160, v173, v160
	v_add_f32_e32 v160, v163, v160
	v_add_f32_e32 v160, v172, v160
	v_add_f32_e32 v160, v164, v160
	s_waitcnt lgkmcnt(2)
	v_mfma_f32_32x32x16_bf16 v[64:79], v[68:71], v[124:127], 0
	v_add_f32_e32 v160, v171, v160
	v_add_f32_e32 v160, v165, v160
	v_add_f32_e32 v160, v170, v160
	v_exp_f32_e32 v156, v156
	v_add_f32_e32 v160, v166, v160
	v_exp_f32_e32 v157, v157
	v_add_f32_e32 v160, v169, v160
	s_waitcnt lgkmcnt(1)
	v_mfma_f32_32x32x16_bf16 v[80:95], v[224:227], v[120:123], v[80:95]
	v_exp_f32_e32 v154, v154
	v_add_f32_e32 v160, v167, v160
	v_exp_f32_e32 v155, v155
	v_add_f32_e32 v160, v168, v160
	v_exp_f32_e32 v148, v148
	v_add_f32_e32 v160, v156, v160
	v_exp_f32_e32 v149, v149
	s_waitcnt lgkmcnt(0)
	v_mfma_f32_32x32x16_bf16 v[64:79], v[236:239], v[120:123], v[64:79]
	ds_read_b128 v[224:227], v221 offset:49152
	ds_read_b128 v[236:239], v221 offset:57344
	v_add_f32_e32 v160, v157, v160
	v_exp_f32_e32 v146, v146
	v_add_f32_e32 v160, v154, v160
	v_exp_f32_e32 v147, v147
	v_add_f32_e32 v160, v155, v160
	v_exp_f32_e32 v144, v144
	s_waitcnt lgkmcnt(1)
	v_mfma_f32_32x32x16_bf16 v[80:95], v[224:227], v[116:119], v[80:95]
	v_add_f32_e32 v160, v148, v160
	v_exp_f32_e32 v145, v145
	v_add_f32_e32 v160, v149, v160
	v_exp_f32_e32 v158, v158
	v_add_f32_e32 v160, v146, v160
	v_exp_f32_e32 v159, v159
	v_add_f32_e32 v160, v147, v160
	s_waitcnt lgkmcnt(0)
	v_mfma_f32_32x32x16_bf16 v[64:79], v[236:239], v[116:119], v[64:79]
	ds_read_b128 v[224:227], v218 offset:49152
	ds_read_b128 v[236:239], v218 offset:57344
	v_exp_f32_e32 v152, v152
	v_add_f32_e32 v160, v144, v160
	v_exp_f32_e32 v153, v153
	v_add_f32_e32 v160, v145, v160
	v_exp_f32_e32 v150, v150
	v_add_f32_e32 v160, v158, v160
	s_waitcnt lgkmcnt(1)
	v_mfma_f32_32x32x16_bf16 v[80:95], v[224:227], v[112:115], v[80:95]
	v_exp_f32_e32 v151, v151
	v_add_f32_e32 v160, v159, v160
	v_add_f32_e32 v160, v152, v160
	v_add_f32_e32 v160, v153, v160
	v_add_f32_e32 v160, v150, v160
	s_waitcnt lgkmcnt(0)
	v_mfma_f32_32x32x16_bf16 v[64:79], v[236:239], v[112:115], v[64:79]
	ds_read_b128 v[224:227], v217 offset:49152
	ds_read_b128 v[236:239], v217 offset:57344
	s_waitcnt lgkmcnt(1)
	v_mfma_f32_32x32x16_bf16 v[80:95], v[224:227], v[108:111], v[80:95]
	s_waitcnt lgkmcnt(0)
	v_mfma_f32_32x32x16_bf16 v[64:79], v[236:239], v[108:111], v[64:79]
	ds_read_b128 v[224:227], v216 offset:49152
	ds_read_b128 v[236:239], v216 offset:57344
	s_waitcnt lgkmcnt(1)
	v_mfma_f32_32x32x16_bf16 v[80:95], v[224:227], v[104:107], v[80:95]
	s_waitcnt lgkmcnt(0)
	v_mfma_f32_32x32x16_bf16 v[64:79], v[236:239], v[104:107], v[64:79]
	ds_read_b128 v[224:227], v219 offset:49152
	ds_read_b128 v[236:239], v219 offset:57344
	s_waitcnt lgkmcnt(1)
	v_mfma_f32_32x32x16_bf16 v[80:95], v[224:227], v[100:103], v[80:95]
	s_waitcnt lgkmcnt(0)
	v_mfma_f32_32x32x16_bf16 v[64:79], v[236:239], v[100:103], v[64:79]
	ds_read_b128 v[224:227], v220 offset:49152
	ds_read_b128 v[236:239], v220 offset:57344
	s_waitcnt lgkmcnt(1)
	v_mfma_f32_32x32x16_bf16 v[80:95], v[224:227], v[96:99], v[80:95]
	v_add_f32_e32 v224, v151, v160
	v_mov_b32_e32 v225, v224
	v_cvt_pk_bf16_f32 v160, v174, v198
	v_cvt_pk_bf16_f32 v161, v161, v175
	v_cvt_pk_bf16_f32 v162, v162, v173
	s_nop 1
	v_permlane32_swap_b32_e32 v224, v225
	s_waitcnt lgkmcnt(0)
; #define SBAR() __builtin_amdgcn_sched_barrier(0)
; __device__ __forceinline__ void partialSM(f32x16& p0, f32x16& p1, float& m_reg, float& mn, float& alpha, bool msk) {
;     constexpr float C = SCALE * 1.4426950408889634f;
;     if (msk) {
; #pragma unroll
;         for (int r = 0; r < 16; ++r) { p0[r] = -1e30f; p1[r] = -1e30f; }
;     }
;     float pmax = p0[0];
; #pragma unroll
;     for (int r = 1; r < 16; ++r) pmax = fmaxf(pmax, p0[r]);
; #pragma unroll
;     for (int r = 0; r < 16; ++r) pmax = fmaxf(pmax, p1[r]);
; template <int D0> __device__ __forceinline__ void pv_one(f32x16& od, int vb, bf16x8 pa0, bf16x8 pa1, bf16x8 pa2, bf16x8 pa3) {
;     const s16x4 l0 = tr_read<v_rd_off(D0, 0, 0)>(vb), h0 = tr_read<v_rd_off(D0, 0, 1)>(vb), l1 = tr_read<v_rd_off(D0, 1, 0)>(vb), h1 = tr_read<v_rd_off(D0, 1, 1)>(vb);
;     const s16x4 l2 = tr_read<v_rd_off(D0, 2, 0)>(vb), h2 = tr_read<v_rd_off(D0, 2, 1)>(vb), l3 = tr_read<v_rd_off(D0, 3, 0)>(vb), h3 = tr_read<v_rd_off(D0, 3, 1)>(vb);
;     asm volatile("s_waitcnt lgkmcnt(0)" ::: "memory"); SBAR();
;     ...
;     od = __builtin_amdgcn_mfma_f32_32x32x16_bf16(pa0, PK(l0, h0), od, 0, 0, 0);
;     od = __builtin_amdgcn_mfma_f32_32x32x16_bf16(pa1, PK(l1, h1), od, 0, 0, 0);
;     od = __builtin_amdgcn_mfma_f32_32x32x16_bf16(pa2, PK(l2, h2), od, 0, 0, 0);
;     od = __builtin_amdgcn_mfma_f32_32x32x16_bf16(pa3, PK(l3, h3), od, 0, 0, 0);
;     ...
; }
; __device__ __forceinline__ void pv_d0(f32x16* o, int vb, bf16x8 pa0, bf16x8 pa1, bf16x8 pa2, bf16x8 pa3) {
;     pv_one<0>(o[0], vb, pa0, pa1, pa2, pa3); pv_one<1>(o[1], vb, pa0, pa1, pa2, pa3); pv_one<2>(o[2], vb, pa0, pa1, pa2, pa3); pv_one<3>(o[3], vb, pa0, pa1, pa2, pa3);
	v_mfma_f32_32x32x16_bf16 v[64:79], v[236:239], v[96:99], v[64:79]
	v_cvt_pk_bf16_f32 v163, v163, v172
	v_permlane32_swap_b32_e32 v160, v162
	v_cvt_pk_bf16_f32 v164, v164, v171
	v_cvt_pk_bf16_f32 v165, v165, v170
	v_cvt_pk_bf16_f32 v166, v166, v169
	v_cvt_pk_bf16_f32 v167, v167, v168
	v_cvt_pk_bf16_f32 v168, v156, v157
	v_cvt_pk_bf16_f32 v169, v154, v155
	v_cvt_pk_bf16_f32 v170, v148, v149
	v_cvt_pk_bf16_f32 v171, v146, v147
	v_cvt_pk_bf16_f32 v172, v144, v145
	v_cvt_pk_bf16_f32 v173, v158, v159
	v_cvt_pk_bf16_f32 v174, v152, v153
	v_cvt_pk_bf16_f32 v175, v150, v151
	v_permlane32_swap_b32_e32 v161, v163
	v_permlane32_swap_b32_e32 v164, v166
	v_permlane32_swap_b32_e32 v165, v167
	v_permlane32_swap_b32_e32 v168, v170
	v_permlane32_swap_b32_e32 v169, v171
	v_permlane32_swap_b32_e32 v172, v174
	v_permlane32_swap_b32_e32 v173, v175
	v_lshl_add_u64 v[200:201], v[192:193], 0, v[188:189]
	s_mov_b32 s10, 0x1d242000
	v_add_co_u32_e32 v144, vcc, s10, v200
	s_mov_b32 s10, 0x1d2a2000
	s_nop 0
	v_addc_co_u32_e32 v145, vcc, 0, v201, vcc
	v_add_co_u32_e32 v148, vcc, s10, v200
	v_lshl_add_u64 v[198:199], v[194:195], 0, v[188:189]
	s_nop 0
	v_addc_co_u32_e32 v149, vcc, 0, v201, vcc
	s_mov_b32 s10, 0x1d241000
	v_add_co_u32_e32 v152, vcc, s10, v198
	s_mov_b32 s10, 0x1d2a1000
	s_nop 0
	v_addc_co_u32_e32 v153, vcc, 0, v199, vcc
	v_add_co_u32_e32 v156, vcc, s10, v198
	global_load_dwordx4 v[144:147], v[144:145], off
	s_nop 0
	global_load_dwordx4 v[148:151], v[148:149], off
	v_addc_co_u32_e32 v157, vcc, 0, v199, vcc
	global_load_dwordx4 v[152:155], v[152:153], off
	s_nop 0
	global_load_dwordx4 v[156:159], v[156:157], off
	ds_read_b64_tr_b16 v[236:237], v209 offset:0
	ds_read_b64_tr_b16 v[238:239], v209 offset:0x800
	ds_read_b64_tr_b16 v[240:241], v209 offset:0x1000
	ds_read_b64_tr_b16 v[242:243], v209 offset:0x1800
	ds_read_b64_tr_b16 v[244:245], v209 offset:0x2000
	ds_read_b64_tr_b16 v[246:247], v209 offset:0x2800
	ds_read_b64_tr_b16 v[248:249], v209 offset:0x3000
	ds_read_b64_tr_b16 v[250:251], v209 offset:0x3800
	s_nop 0
	s_waitcnt lgkmcnt(6)
	v_mfma_f32_32x32x16_bf16 v[0:15], v[160:163], v[236:239], v[0:15]
	ds_read_b64_tr_b16 v[236:237], v209 offset:0x200
	ds_read_b64_tr_b16 v[238:239], v209 offset:0xa00
	s_waitcnt lgkmcnt(6)
	v_mfma_f32_32x32x16_bf16 v[0:15], v[164:167], v[240:243], v[0:15]
	ds_read_b64_tr_b16 v[240:241], v209 offset:0x1200
	ds_read_b64_tr_b16 v[242:243], v209 offset:0x1a00
	s_waitcnt lgkmcnt(6)
	v_mfma_f32_32x32x16_bf16 v[0:15], v[168:171], v[244:247], v[0:15]
	ds_read_b64_tr_b16 v[244:245], v209 offset:0x2200
	ds_read_b64_tr_b16 v[246:247], v209 offset:0x2a00
	s_waitcnt lgkmcnt(6)
	v_mfma_f32_32x32x16_bf16 v[0:15], v[172:175], v[248:251], v[0:15]
	ds_read_b64_tr_b16 v[248:249], v209 offset:0x3200
	ds_read_b64_tr_b16 v[250:251], v209 offset:0x3a00
	s_waitcnt lgkmcnt(6)
	v_mfma_f32_32x32x16_bf16 v[48:63], v[160:163], v[236:239], v[48:63]
	ds_read_b64_tr_b16 v[236:237], v209 offset:0x400
	ds_read_b64_tr_b16 v[238:239], v209 offset:0xc00
	s_waitcnt lgkmcnt(6)
	v_mfma_f32_32x32x16_bf16 v[48:63], v[164:167], v[240:243], v[48:63]
	ds_read_b64_tr_b16 v[240:241], v209 offset:0x1400
	ds_read_b64_tr_b16 v[242:243], v209 offset:0x1c00
	s_waitcnt lgkmcnt(6)
	v_mfma_f32_32x32x16_bf16 v[48:63], v[168:171], v[244:247], v[48:63]
	ds_read_b64_tr_b16 v[244:245], v209 offset:0x2400
	ds_read_b64_tr_b16 v[246:247], v209 offset:0x2c00
	s_waitcnt lgkmcnt(6)
	v_mfma_f32_32x32x16_bf16 v[48:63], v[172:175], v[248:251], v[48:63]
	ds_read_b64_tr_b16 v[248:249], v209 offset:0x3400
	ds_read_b64_tr_b16 v[250:251], v209 offset:0x3c00
	s_waitcnt lgkmcnt(6)
	v_mfma_f32_32x32x16_bf16 v[32:47], v[160:163], v[236:239], v[32:47]
	ds_read_b64_tr_b16 v[236:237], v209 offset:0x600
	ds_read_b64_tr_b16 v[238:239], v209 offset:0xe00
	s_waitcnt lgkmcnt(6)
	v_mfma_f32_32x32x16_bf16 v[32:47], v[164:167], v[240:243], v[32:47]
	ds_read_b64_tr_b16 v[240:241], v209 offset:0x1600
	ds_read_b64_tr_b16 v[242:243], v209 offset:0x1e00
	s_waitcnt lgkmcnt(6)
	v_mfma_f32_32x32x16_bf16 v[32:47], v[168:171], v[244:247], v[32:47]
	ds_read_b64_tr_b16 v[244:245], v209 offset:0x2600
	ds_read_b64_tr_b16 v[246:247], v209 offset:0x2e00
	s_waitcnt lgkmcnt(6)
	v_mfma_f32_32x32x16_bf16 v[32:47], v[172:175], v[248:251], v[32:47]
	ds_read_b64_tr_b16 v[248:249], v209 offset:0x3600
	ds_read_b64_tr_b16 v[250:251], v209 offset:0x3e00
	s_waitcnt lgkmcnt(0)
	v_mfma_f32_32x32x16_bf16 v[16:31], v[160:163], v[236:239], v[16:31]
	s_cmp_gt_i32 s9, s45
	s_cbranch_scc1 .Lattn_mask_0
	v_mov_b32_e32 v160, v80
	v_mov_b32_e32 v80, v76
	v_mov_b32_e32 v76, v77
	v_max_f32_e32 v77, v81, v81
	v_mfma_f32_32x32x16_bf16 v[16:31], v[164:167], v[240:243], v[16:31]
	v_max_f32_e32 v161, v160, v160
	v_max_f32_e32 v77, v161, v77
	v_max3_f32 v77, v77, v82, v83
	v_max3_f32 v77, v77, v84, v85
	v_max3_f32 v77, v77, v86, v87
	v_max3_f32 v77, v77, v88, v89
	v_max3_f32 v77, v77, v90, v91
	v_max3_f32 v77, v77, v92, v93
	v_mfma_f32_32x32x16_bf16 v[16:31], v[168:171], v[244:247], v[16:31]
	v_max3_f32 v77, v77, v94, v95
	v_max3_f32 v77, v77, v64, v65
	v_max3_f32 v77, v77, v66, v67
	v_max3_f32 v77, v77, v68, v69
	v_max3_f32 v77, v77, v70, v71
	v_max3_f32 v77, v77, v72, v73
	v_max3_f32 v77, v77, v74, v75

; #define SBAR() __builtin_amdgcn_sched_barrier(0)
; __device__ __forceinline__ void partialSM(f32x16& p0, f32x16& p1, float& m_reg, float& mn, float& alpha, bool msk) {
;     constexpr float C = SCALE * 1.4426950408889634f;
;     if (msk) {
; #pragma unroll
;         for (int r = 0; r < 16; ++r) { p0[r] = -1e30f; p1[r] = -1e30f; }
;     }
;     float pmax = p0[0];
; #pragma unroll
;     for (int r = 1; r < 16; ++r) pmax = fmaxf(pmax, p0[r]);
; #pragma unroll
;     for (int r = 0; r < 16; ++r) pmax = fmaxf(pmax, p1[r]);
; template <int D0> __device__ __forceinline__ void pv_one(f32x16& od, int vb, bf16x8 pa0, bf16x8 pa1, bf16x8 pa2, bf16x8 pa3) {
;     const s16x4 l0 = tr_read<v_rd_off(D0, 0, 0)>(vb), h0 = tr_read<v_rd_off(D0, 0, 1)>(vb), l1 = tr_read<v_rd_off(D0, 1, 0)>(vb), h1 = tr_read<v_rd_off(D0, 1, 1)>(vb);
;     const s16x4 l2 = tr_read<v_rd_off(D0, 2, 0)>(vb), h2 = tr_read<v_rd_off(D0, 2, 1)>(vb), l3 = tr_read<v_rd_off(D0, 3, 0)>(vb), h3 = tr_read<v_rd_off(D0, 3, 1)>(vb);
;     asm volatile("s_waitcnt lgkmcnt(0)" ::: "memory"); SBAR();
;     ...
;     od = __builtin_amdgcn_mfma_f32_32x32x16_bf16(pa0, PK(l0, h0), od, 0, 0, 0);
;     od = __builtin_amdgcn_mfma_f32_32x32x16_bf16(pa1, PK(l1, h1), od, 0, 0, 0);
;     od = __builtin_amdgcn_mfma_f32_32x32x16_bf16(pa2, PK(l2, h2), od, 0, 0, 0);
;     od = __builtin_amdgcn_mfma_f32_32x32x16_bf16(pa3, PK(l3, h3), od, 0, 0, 0);
;     ...
; }
; __device__ __forceinline__ void pv_d0(f32x16* o, int vb, bf16x8 pa0, bf16x8 pa1, bf16x8 pa2, bf16x8 pa3) {
;     pv_one<0>(o[0], vb, pa0, pa1, pa2, pa3); pv_one<1>(o[1], vb, pa0, pa1, pa2, pa3); pv_one<2>(o[2], vb, pa0, pa1, pa2, pa3); pv_one<3>(o[3], vb, pa0, pa1, pa2, pa3);
.LBB0_287:
	ds_read_b64_tr_b16 v[198:199], v208 offset:0
	ds_read_b64_tr_b16 v[200:201], v208 offset:0x800
	ds_read_b64_tr_b16 v[230:231], v208 offset:0x1000
	ds_read_b64_tr_b16 v[232:233], v208 offset:0x1800
	ds_read_b64_tr_b16 v[236:237], v208 offset:0x2000
	ds_read_b64_tr_b16 v[238:239], v208 offset:0x2800
	ds_read_b64_tr_b16 v[240:241], v208 offset:0x3000
	ds_read_b64_tr_b16 v[242:243], v208 offset:0x3800
	s_nop 0
	s_waitcnt lgkmcnt(6)
	v_mfma_f32_32x32x16_bf16 v[0:15], v[160:163], v[198:201], v[0:15]
	ds_read_b64_tr_b16 v[198:199], v208 offset:0x200
	ds_read_b64_tr_b16 v[200:201], v208 offset:0xa00
	s_waitcnt lgkmcnt(6)
	v_mfma_f32_32x32x16_bf16 v[0:15], v[164:167], v[230:233], v[0:15]
	ds_read_b64_tr_b16 v[230:231], v208 offset:0x1200
	ds_read_b64_tr_b16 v[232:233], v208 offset:0x1a00
	s_waitcnt lgkmcnt(6)
	v_mfma_f32_32x32x16_bf16 v[0:15], v[168:171], v[236:239], v[0:15]
	ds_read_b64_tr_b16 v[236:237], v208 offset:0x2200
	ds_read_b64_tr_b16 v[238:239], v208 offset:0x2a00
	s_waitcnt lgkmcnt(6)
	v_mfma_f32_32x32x16_bf16 v[0:15], v[172:175], v[240:243], v[0:15]
	ds_read_b64_tr_b16 v[240:241], v208 offset:0x3200
	ds_read_b64_tr_b16 v[242:243], v208 offset:0x3a00
	s_waitcnt lgkmcnt(6)
	v_mfma_f32_32x32x16_bf16 v[48:63], v[160:163], v[198:201], v[48:63]
	ds_read_b64_tr_b16 v[198:199], v208 offset:0x400
	ds_read_b64_tr_b16 v[200:201], v208 offset:0xc00
	s_waitcnt lgkmcnt(6)
	v_mfma_f32_32x32x16_bf16 v[48:63], v[164:167], v[230:233], v[48:63]
	ds_read_b64_tr_b16 v[230:231], v208 offset:0x1400
	ds_read_b64_tr_b16 v[232:233], v208 offset:0x1c00
	s_waitcnt lgkmcnt(6)
	v_mfma_f32_32x32x16_bf16 v[48:63], v[168:171], v[236:239], v[48:63]
	ds_read_b64_tr_b16 v[236:237], v208 offset:0x2400
	ds_read_b64_tr_b16 v[238:239], v208 offset:0x2c00
	s_waitcnt lgkmcnt(6)
	v_mfma_f32_32x32x16_bf16 v[48:63], v[172:175], v[240:243], v[48:63]
	ds_read_b64_tr_b16 v[240:241], v208 offset:0x3400
	ds_read_b64_tr_b16 v[242:243], v208 offset:0x3c00
	s_waitcnt lgkmcnt(6)
	v_mfma_f32_32x32x16_bf16 v[32:47], v[160:163], v[198:201], v[32:47]
	ds_read_b64_tr_b16 v[198:199], v208 offset:0x600
	ds_read_b64_tr_b16 v[200:201], v208 offset:0xe00
	s_waitcnt lgkmcnt(6)
	v_mfma_f32_32x32x16_bf16 v[32:47], v[164:167], v[230:233], v[32:47]
	ds_read_b64_tr_b16 v[230:231], v208 offset:0x1600
	ds_read_b64_tr_b16 v[232:233], v208 offset:0x1e00
	s_waitcnt lgkmcnt(6)
	v_mfma_f32_32x32x16_bf16 v[32:47], v[168:171], v[236:239], v[32:47]
	ds_read_b64_tr_b16 v[236:237], v208 offset:0x2600
	ds_read_b64_tr_b16 v[238:239], v208 offset:0x2e00
	s_waitcnt lgkmcnt(6)
	v_mfma_f32_32x32x16_bf16 v[32:47], v[172:175], v[240:243], v[32:47]
	ds_read_b64_tr_b16 v[240:241], v208 offset:0x3600
	ds_read_b64_tr_b16 v[242:243], v208 offset:0x3e00
	s_waitcnt lgkmcnt(0)
	v_mfma_f32_32x32x16_bf16 v[16:31], v[160:163], v[198:201], v[16:31]
	s_cmp_gt_i32 s25, s45
	s_cbranch_scc1 .Lattn_mask_1
	v_max_f32_e32 v160, v81, v81
	v_max_f32_e32 v161, v80, v80
	v_mfma_f32_32x32x16_bf16 v[16:31], v[164:167], v[230:233], v[16:31]
	v_max_f32_e32 v160, v161, v160
	v_max3_f32 v160, v160, v82, v83
	v_max3_f32 v160, v160, v84, v85
	v_max3_f32 v160, v160, v86, v87
	v_max3_f32 v160, v160, v88, v89
	v_max3_f32 v160, v160, v90, v91
	v_max3_f32 v160, v160, v92, v93
	v_mfma_f32_32x32x16_bf16 v[16:31], v[168:171], v[236:239], v[16:31]
	v_max3_f32 v160, v160, v94, v95
	v_max3_f32 v160, v160, v64, v65
	v_max3_f32 v160, v160, v66, v67
	v_max3_f32 v160, v160, v68, v69
	v_max3_f32 v160, v160, v70, v71
	v_max3_f32 v160, v160, v72, v73
	v_max3_f32 v160, v160, v74, v75
